# ATTN: next unit's skip-count load no longer waited with vmcnt(0) at the unit top; consumed at the unit end
# speedup vs baseline: 1.0012x; 1.0012x over previous
.LBB0_588:
	s_or_b64 exec, exec, s[2:3]
	s_waitcnt lgkmcnt(0)
	ds_read_b128 v[32:35], v65 offset:49280
	ds_read_b128 v[36:39], v65 offset:49312
	s_and_b64 s[2:3], s[52:53], exec
	s_cselect_b32 s82, s72, s82
	s_cselect_b32 s90, s83, s90
	s_waitcnt lgkmcnt(1)
	v_rcp_f32_e32 v40, v32
	s_lshl_b32 s2, s71, 12
	v_rcp_f32_e32 v41, v33
	s_add_i32 s2, s2, 0
	v_lshlrev_b32_e32 v48, 1, v204
	v_mul_f32_e32 v0, v0, v40
	v_add3_u32 v48, s2, v48, v243
	v_cvt_pk_bf16_f32 v0, v0, s0
	v_rcp_f32_e32 v42, v34
	v_rcp_f32_e32 v43, v35
	s_waitcnt lgkmcnt(0)
	v_rcp_f32_e32 v44, v36
	ds_read_b128 v[32:35], v65 offset:49344
	v_rcp_f32_e32 v45, v37
	v_rcp_f32_e32 v46, v38
	v_rcp_f32_e32 v47, v39
	ds_read_b128 v[36:39], v65 offset:49376
	ds_write_b16 v48, v0 offset:51200
	v_mul_f32_e32 v0, v16, v40
	v_cvt_pk_bf16_f32 v0, v0, s0
	ds_write_b16 v48, v0 offset:51264
	v_mul_f32_e32 v0, v1, v41
	v_cvt_pk_bf16_f32 v0, v0, s0
	ds_write_b16 v48, v0 offset:51328
	v_mul_f32_e32 v0, v17, v41
	v_cvt_pk_bf16_f32 v0, v0, s0
	ds_write_b16 v48, v0 offset:51392
	v_mul_f32_e32 v0, v2, v42
	v_cvt_pk_bf16_f32 v0, v0, s0
	ds_write_b16 v48, v0 offset:51456
	v_mul_f32_e32 v0, v18, v42
	v_cvt_pk_bf16_f32 v0, v0, s0
	ds_write_b16 v48, v0 offset:51520
	v_mul_f32_e32 v0, v3, v43
	v_cvt_pk_bf16_f32 v0, v0, s0
	ds_write_b16 v48, v0 offset:51584
	v_mul_f32_e32 v0, v19, v43
	v_cvt_pk_bf16_f32 v0, v0, s0
	ds_write_b16 v48, v0 offset:51648
	v_mul_f32_e32 v0, v4, v44
	v_cvt_pk_bf16_f32 v0, v0, s0
	ds_write_b16 v48, v0 offset:52224
	v_mul_f32_e32 v0, v20, v44
	v_cvt_pk_bf16_f32 v0, v0, s0
	ds_write_b16 v48, v0 offset:52288
	v_mul_f32_e32 v0, v5, v45
	v_cvt_pk_bf16_f32 v0, v0, s0
	ds_write_b16 v48, v0 offset:52352
	v_mul_f32_e32 v0, v21, v45
	v_cvt_pk_bf16_f32 v0, v0, s0
	ds_write_b16 v48, v0 offset:52416
	v_mul_f32_e32 v0, v6, v46
	v_cvt_pk_bf16_f32 v0, v0, s0
	ds_write_b16 v48, v0 offset:52480
	v_mul_f32_e32 v0, v22, v46
	v_cvt_pk_bf16_f32 v0, v0, s0
	s_waitcnt lgkmcnt(14)
	v_rcp_f32_e32 v32, v32
	ds_write_b16 v48, v0 offset:52544
	v_mul_f32_e32 v0, v7, v47
	v_cvt_pk_bf16_f32 v0, v0, s0
	ds_write_b16 v48, v0 offset:52608
	v_mul_f32_e32 v0, v23, v47
	v_cvt_pk_bf16_f32 v0, v0, s0
	v_rcp_f32_e32 v33, v33
	ds_write_b16 v48, v0 offset:52672
	v_mul_f32_e32 v0, v8, v32
	v_cvt_pk_bf16_f32 v0, v0, s0
	ds_write_b16 v48, v0 offset:53248
	v_mul_f32_e32 v0, v24, v32
	v_cvt_pk_bf16_f32 v0, v0, s0
	v_rcp_f32_e32 v34, v34
	ds_write_b16 v48, v0 offset:53312
	v_mul_f32_e32 v0, v9, v33
	v_cvt_pk_bf16_f32 v0, v0, s0
	ds_write_b16 v48, v0 offset:53376
	v_mul_f32_e32 v0, v25, v33
	v_cvt_pk_bf16_f32 v0, v0, s0
	v_rcp_f32_e32 v35, v35
	ds_write_b16 v48, v0 offset:53440
	v_mul_f32_e32 v0, v10, v34
	v_cvt_pk_bf16_f32 v0, v0, s0
	ds_write_b16 v48, v0 offset:53504
	v_mul_f32_e32 v0, v26, v34
	v_cvt_pk_bf16_f32 v0, v0, s0
	s_waitcnt lgkmcnt(14)
	v_rcp_f32_e32 v36, v36
	ds_write_b16 v48, v0 offset:53568
	v_mul_f32_e32 v0, v11, v35
	v_cvt_pk_bf16_f32 v0, v0, s0
	ds_write_b16 v48, v0 offset:53632
	v_mul_f32_e32 v0, v27, v35
	v_cvt_pk_bf16_f32 v0, v0, s0
	v_rcp_f32_e32 v37, v37
	ds_write_b16 v48, v0 offset:53696
	v_mul_f32_e32 v0, v12, v36
	v_cvt_pk_bf16_f32 v0, v0, s0
	ds_write_b16 v48, v0 offset:54272
	v_mul_f32_e32 v0, v28, v36
	v_cvt_pk_bf16_f32 v0, v0, s0
	v_rcp_f32_e32 v38, v38
	ds_write_b16 v48, v0 offset:54336
	v_mul_f32_e32 v0, v13, v37
	v_cvt_pk_bf16_f32 v0, v0, s0
	ds_write_b16 v48, v0 offset:54400
	v_mul_f32_e32 v0, v29, v37
	v_cvt_pk_bf16_f32 v0, v0, s0
	v_rcp_f32_e32 v39, v39
	ds_write_b16 v48, v0 offset:54464
	v_mul_f32_e32 v0, v14, v38
	v_cvt_pk_bf16_f32 v0, v0, s0
	ds_write_b16 v48, v0 offset:54528
	v_mul_f32_e32 v0, v30, v38
	v_cvt_pk_bf16_f32 v0, v0, s0
	s_lshl_b64 s[52:53], s[58:59], 1
	ds_write_b16 v48, v0 offset:54592
	v_mul_f32_e32 v0, v15, v39
	s_add_u32 s3, s70, s52
	v_cvt_pk_bf16_f32 v0, v0, s0
	s_addc_u32 s6, s77, s53
	ds_write_b16 v48, v0 offset:54656
	v_mul_f32_e32 v0, v31, v39
	s_add_u32 s18, s3, s18
	v_cvt_pk_bf16_f32 v0, v0, s0
	s_addc_u32 s19, s6, s19
	v_mov_b32_e32 v189, v101
	ds_write_b16 v48, v0 offset:54720
	v_lshl_add_u64 v[16:17], s[18:19], 0, v[188:189]
	v_mov_b32_e32 v191, v101
	s_waitcnt lgkmcnt(0)
	v_lshl_add_u64 v[0:1], v[16:17], 0, v[190:191]
	global_load_dwordx4 v[0:3], v[0:1], off
	v_mov_b32_e32 v193, v101
	v_lshl_add_u64 v[4:5], v[16:17], 0, v[192:193]
	global_load_dwordx4 v[4:7], v[4:5], off
	v_mov_b32_e32 v195, v101
	v_lshl_add_u64 v[8:9], v[16:17], 0, v[194:195]
	global_load_dwordx4 v[8:11], v[8:9], off
	v_add_u32_e32 v26, s2, v188
	v_add_u32_e32 v12, v26, v244
	ds_read_b128 v[12:15], v12 offset:51200
	v_mov_b32_e32 v197, v101
	v_lshl_add_u64 v[16:17], v[16:17], 0, v[196:197]
	v_lshl_add_u64 v[20:21], s[14:15], 0, v[188:189]
	s_cmp_lg_u32 s91, 4
	s_waitcnt lgkmcnt(0)
	v_lshlrev_b32_e32 v18, 16, v12
	v_and_b32_e32 v19, 0xffff0000, v12
	v_lshlrev_b32_e32 v12, 16, v13
	v_and_b32_e32 v13, 0xffff0000, v13
	s_waitcnt vmcnt(4)
	v_readfirstlane_b32 s92, v251
	s_nop 1
	s_mov_b32 s2, s92
	s_waitcnt vmcnt(2)
	v_lshlrev_b32_e32 v22, 16, v0
	v_and_b32_e32 v23, 0xffff0000, v0
	v_pk_mul_f32 v[18:19], v[18:19], v[22:23]
	v_lshlrev_b32_e32 v22, 16, v1
	v_cvt_pk_bf16_f32 v0, v18, v19
	global_load_dwordx4 v[16:19], v[16:17], off
	v_and_b32_e32 v23, 0xffff0000, v1
	v_pk_mul_f32 v[12:13], v[12:13], v[22:23]
	v_lshlrev_b32_e32 v22, 16, v2
	v_cvt_pk_bf16_f32 v1, v12, v13
	v_lshlrev_b32_e32 v12, 16, v14
	v_and_b32_e32 v13, 0xffff0000, v14
	v_and_b32_e32 v23, 0xffff0000, v2
	v_pk_mul_f32 v[12:13], v[12:13], v[22:23]
	v_lshlrev_b32_e32 v24, 16, v3
	v_and_b32_e32 v25, 0xffff0000, v3
	v_add_u32_e32 v3, v26, v245
	v_cvt_pk_bf16_f32 v2, v12, v13
	v_lshlrev_b32_e32 v22, 16, v15
	v_and_b32_e32 v23, 0xffff0000, v15
	ds_read_b128 v[12:15], v3 offset:51200
	v_pk_mul_f32 v[22:23], v[22:23], v[24:25]
	s_nop 0
	v_cvt_pk_bf16_f32 v3, v22, v23
	v_lshl_add_u64 v[22:23], v[20:21], 0, v[190:191]
	global_store_dwordx4 v[22:23], v[0:3], off
	s_waitcnt lgkmcnt(0)
	s_nop 0
	v_lshlrev_b32_e32 v0, 16, v12
	v_and_b32_e32 v1, 0xffff0000, v12
	s_waitcnt vmcnt(3)
	v_lshlrev_b32_e32 v2, 16, v4
	v_and_b32_e32 v3, 0xffff0000, v4
	v_pk_mul_f32 v[0:1], v[0:1], v[2:3]
	v_lshlrev_b32_e32 v2, 16, v13
	v_and_b32_e32 v3, 0xffff0000, v13
	v_lshlrev_b32_e32 v4, 16, v5
	v_and_b32_e32 v5, 0xffff0000, v5
	v_pk_mul_f32 v[2:3], v[2:3], v[4:5]
	v_cvt_pk_bf16_f32 v0, v0, v1
	v_cvt_pk_bf16_f32 v1, v2, v3
	v_lshlrev_b32_e32 v2, 16, v14
	v_and_b32_e32 v3, 0xffff0000, v14
	v_lshlrev_b32_e32 v4, 16, v6
	v_and_b32_e32 v5, 0xffff0000, v6
	v_pk_mul_f32 v[2:3], v[2:3], v[4:5]
	v_lshlrev_b32_e32 v12, 16, v15
	v_cvt_pk_bf16_f32 v2, v2, v3
	v_add_u32_e32 v3, v26, v246
	v_and_b32_e32 v13, 0xffff0000, v15
	v_lshlrev_b32_e32 v14, 16, v7
	v_and_b32_e32 v15, 0xffff0000, v7
	ds_read_b128 v[4:7], v3 offset:51200
	v_pk_mul_f32 v[12:13], v[12:13], v[14:15]
	s_nop 0
	v_cvt_pk_bf16_f32 v3, v12, v13
	v_lshl_add_u64 v[12:13], v[20:21], 0, v[192:193]
	global_store_dwordx4 v[12:13], v[0:3], off
	s_waitcnt lgkmcnt(0)
	s_nop 0
	v_lshlrev_b32_e32 v0, 16, v4
	v_and_b32_e32 v1, 0xffff0000, v4
	s_waitcnt vmcnt(3)
	v_lshlrev_b32_e32 v2, 16, v8
	v_and_b32_e32 v3, 0xffff0000, v8
	v_pk_mul_f32 v[0:1], v[0:1], v[2:3]
	v_lshlrev_b32_e32 v2, 16, v5
	v_and_b32_e32 v3, 0xffff0000, v5
	v_lshlrev_b32_e32 v4, 16, v9
	v_and_b32_e32 v5, 0xffff0000, v9
	v_pk_mul_f32 v[2:3], v[2:3], v[4:5]
	v_cvt_pk_bf16_f32 v0, v0, v1
	v_cvt_pk_bf16_f32 v1, v2, v3
	v_lshlrev_b32_e32 v2, 16, v6
	v_and_b32_e32 v3, 0xffff0000, v6
	v_lshlrev_b32_e32 v4, 16, v10
	v_and_b32_e32 v5, 0xffff0000, v10
	v_pk_mul_f32 v[2:3], v[2:3], v[4:5]
	v_lshlrev_b32_e32 v8, 16, v7
	v_cvt_pk_bf16_f32 v2, v2, v3
	v_add_u32_e32 v3, v26, v247
	v_and_b32_e32 v9, 0xffff0000, v7
	ds_read_b128 v[4:7], v3 offset:51200
	v_lshlrev_b32_e32 v10, 16, v11
	v_and_b32_e32 v11, 0xffff0000, v11
	v_pk_mul_f32 v[8:9], v[8:9], v[10:11]
	s_nop 0
	v_cvt_pk_bf16_f32 v3, v8, v9
	v_lshl_add_u64 v[8:9], v[20:21], 0, v[194:195]
	global_store_dwordx4 v[8:9], v[0:3], off
	s_waitcnt lgkmcnt(0)
	s_nop 0
	v_lshlrev_b32_e32 v0, 16, v4
	v_and_b32_e32 v1, 0xffff0000, v4
	s_waitcnt vmcnt(3)
	v_lshlrev_b32_e32 v2, 16, v16
	v_and_b32_e32 v3, 0xffff0000, v16
	v_pk_mul_f32 v[0:1], v[0:1], v[2:3]
	v_lshlrev_b32_e32 v2, 16, v5
	v_and_b32_e32 v3, 0xffff0000, v5
	v_lshlrev_b32_e32 v4, 16, v17
	v_and_b32_e32 v5, 0xffff0000, v17
	v_pk_mul_f32 v[2:3], v[2:3], v[4:5]
	v_cvt_pk_bf16_f32 v0, v0, v1
	v_cvt_pk_bf16_f32 v1, v2, v3
	v_lshlrev_b32_e32 v2, 16, v6
	v_and_b32_e32 v3, 0xffff0000, v6
	v_lshlrev_b32_e32 v4, 16, v18
	v_and_b32_e32 v5, 0xffff0000, v18
	v_pk_mul_f32 v[2:3], v[2:3], v[4:5]
	v_lshlrev_b32_e32 v4, 16, v7
	v_and_b32_e32 v5, 0xffff0000, v7
	v_lshlrev_b32_e32 v6, 16, v19
	v_and_b32_e32 v7, 0xffff0000, v19
	v_pk_mul_f32 v[4:5], v[4:5], v[6:7]
	v_cvt_pk_bf16_f32 v2, v2, v3
	v_cvt_pk_bf16_f32 v3, v4, v5
	v_lshl_add_u64 v[4:5], v[20:21], 0, v[196:197]
	global_store_dwordx4 v[4:5], v[0:3], off
	s_waitcnt lgkmcnt(0)
	s_barrier
	s_cbranch_scc0 .LBB0_672
.LBB0_589:
	s_mov_b32 s3, s91
	s_add_i32 s91, s91, 1
	s_cmp_lt_u32 s3, 3
	s_cselect_b64 s[52:53], -1, 0
	s_cmp_eq_u32 s91, 2
	s_cselect_b32 s6, s85, s86
	s_cmp_eq_u32 s3, 0
	s_cselect_b32 s72, s87, s6
	s_cmp_gt_u32 s3, 2
	s_mov_b32 s92, s2
	s_cbranch_scc1 .LBB0_591
	s_or_b32 s14, s72, s84
	s_ashr_i32 s15, s14, 31
	s_lshl_b64 s[14:15], s[14:15], 2
	s_add_u32 s14, s80, s14
	s_addc_u32 s15, s81, s15
	global_load_dword v251, v101, s[14:15]
